# free-slack start offsets retuned: in-proj L0 7 sleeps, out-proj L0 8 sleeps
# baseline (speedup 1.0000x reference)
; template <int EPI>
; DI bool tile_coords(int j, int mpx, int& m0, int& n0) {
;     ...
;   } else {
;     if (q >= mpx * 4) return false;
;     m0 = (x * mpx + (q >> 2)) * 256;
;     n0 = (q & 3) * 256;
;   }
; DI void phase_outproj(const P& p, int l, char* lds) {
;   const int mrows = (l == 0) ? MALL : MLAT;
;   gemm_phase<1>(p, l, p.H  , p.Wot + (size_t)l * 1024 * 1024, (mrows / 256) / 8, lds);
.LBB0_66:
	s_andn2_b64 vcc, exec, s[0:1]
	s_cbranch_vccnz .LBB0_73
	s_cmp_lt_u32 s23, 4
	s_cselect_b64 s[0:1], -1, 0
	s_and_b64 s[26:27], s[0:1], exec
	s_cselect_b32 s2, 18, 16
	s_lshl_b32 s25, s2, 2
	s_cmp_lt_u32 s84, s25
	v_mov_b32_e32 v0, v195
	s_cbranch_scc0 .LBB0_73
	s_cmp_lg_u32 s50, 0
	s_cbranch_scc1 .Ldephase_out_done
	s_cmp_lt_u32 s84, 8
	s_cbranch_scc1 .Ldephase_out_done
	s_sleep 127
	s_sleep 127
	s_sleep 127
	s_sleep 127
	s_sleep 127
	s_sleep 127
	s_sleep 127
	s_sleep 127

; template <int EPI>
; DI bool tile_coords(int j, int mpx, int& m0, int& n0) {
;     ...
;   if constexpr (EPI == 0) {
;     if (q >= mpx * 15) return false;
;     const int panel = q / 90, i = q % 90;
;     const int nt = i / 6, mi = i % 6;
;     m0 = (x * mpx + panel * 6 + mi) * 256;
;     n0 = nt * 256;
; DI void phase_inproj(const P& p, int l, char* lds) {
;   gemm_phase<0>(p, l, p.H, p.Wt + (size_t)l * NIN * 1024, (MALL / 256) / 8, lds);
.LBB0_74:
	s_andn2_b64 vcc, exec, s[0:1]
	s_cbranch_vccnz .LBB0_941
	s_cmp_lg_u32 s24, 1
	s_mov_b64 s[0:1], -1
	s_cbranch_scc0 .LBB0_812
	v_readlane_b32 s0, v254, 9
	v_readlane_b32 s1, v254, 10
	v_mov_b32_e32 v0, v195
	s_andn2_b64 vcc, exec, s[0:1]
	s_cbranch_vccnz .LBB0_811
	s_cmp_lg_u32 s50, 0
	s_cbranch_scc1 .Ldephase_in_done
	s_cmp_lt_u32 s84, 14
	s_cbranch_scc1 .Ldephase_in_done
	s_sleep 127
	s_sleep 127
	s_sleep 127
	s_sleep 127
	s_sleep 127
	s_sleep 127
	s_sleep 127
